# plus: SWA key-position loads hoisted to tile-loop top; skip redundant cg grid.sync; drop over-conservative vmcnt waits in MLA prefetch
# speedup vs baseline: 1.0065x; 1.0065x over previous
; __global__ void __launch_bounds__(512) mega_fwd(Params p) {
;     ...
;     XcdBarrier xbar = xcd_barrier_post((unsigned*)(p.ws), xst);
;     phase_tables(C, p);
;     asm volatile("s_waitcnt vmcnt(0) lgkmcnt(0)" ::: "memory"); grid.sync();
.LBB0_13:
	s_or_b64 exec, exec, s[0:1]
	v_lshrrev_b32_e32 v1, 20, v0
	v_lshrrev_b32_e32 v0, 10, v0
	s_waitcnt vmcnt(0) lgkmcnt(0)
	v_or_b32_e32 v0, v0, v1
	s_movk_i32 s0, 0x3ff
	v_and_or_b32 v0, v0, s0, v174
	v_cmp_eq_u32_e32 vcc, 0, v0
	s_barrier
	s_and_saveexec_b64 s[0:1], vcc
	s_branch .LBB0_23
	buffer_wbl2 sc1
	s_waitcnt vmcnt(0)
	s_load_dwordx2 s[2:3], s[2:3], 0x58
	v_mov_b32_e32 v2, 0
	s_mov_b64 s[4:5], exec
	v_mbcnt_lo_u32_b32 v1, s4, 0
	v_mbcnt_hi_u32_b32 v1, s5, v1
	s_waitcnt lgkmcnt(0)
	global_load_dword v0, v2, s[2:3] offset:40
	v_cmp_eq_u32_e32 vcc, 0, v1
	s_and_saveexec_b64 s[6:7], vcc
	s_cbranch_execz .LBB0_16
	s_bcnt1_i32_b64 s4, s[4:5]
	v_mov_b32_e32 v3, s4
	global_atomic_add v3, v2, v3, s[2:3] offset:32 sc0

; #define LAS __attribute__((address_space(3)))
; __device__ __forceinline__ void swa_unit(const Ctx& C, const Params& p, int l, int unit) {
;     ...
;             const LAS unsigned char* Kb = lds + (kt - kt_lo) * STILE; const LAS unsigned char* Vb = Kb + 64 * SROW;
;             const int k0 = kt * 64;
;             f32x4 s[2][4];
; #pragma unroll
;             for (int blk = 0; blk < 4; ++blk) {
;                 bf16x8 kf[2];
; #pragma unroll
;                 for (int kk = 0; kk < 2; ++kk) kf[kk] = *(const LAS bf16x8*)(Kb + (blk * 16 + fr) * SROW + (kk * 32 + fq * 8) * 2);
; #pragma unroll
;                 for (int g = 0; g < 2; ++g) { f32x4 a = (f32x4){0.f, 0.f, 0.f, 0.f};
; #pragma unroll
;                     for (int kk = 0; kk < 2; ++kk) a = __builtin_amdgcn_mfma_f32_16x16x32_bf16(kf[kk], qf[g][kk], a, 0, 0, 0);
;                     s[g][blk] = a; }
;             }
;             bf16x8 pf[2][2];
; #pragma unroll
;             for (int g = 0; g < 2; ++g) {
;                 const int qi = q0w + 16 * g + fr;
; #pragma unroll
;                 for (int blk = 0; blk < 4; ++blk) { const int4 t4 = *(const int4*)(p.pos + tok0 + k0 + blk * 16 + fq * 4); const int pkv[4] = {t4.x, t4.y, t4.z, t4.w};
; #pragma unroll
;                     for (int j = 0; j < 4; ++j) { const int key = k0 + blk * 16 + fq * 4 + j; int dd = pq[g] - pkv[j]; dd = dd < 0 ? 0 : (dd > 128 ? 128 : dd);
;                         const float v = s[g][blk][j] * c2 + bth[dd]; const bool ok = (key <= qi) && (qi - key < 128); s[g][blk][j] = ok ? v : -1e30f; } }
.LBB0_276:
	global_load_dwordx4 v[198:201], v[102:103], off
	global_load_dwordx4 v[202:205], v[102:103], off offset:64
	global_load_dwordx4 v[206:209], v[102:103], off offset:128
	global_load_dwordx4 v[210:213], v[102:103], off offset:192
	ds_read_b128 v[50:53], v126
	s_nop 0
	ds_read_b128 v[54:57], v126 offset:64
	v_mov_b32_e32 v129, v66
	v_mov_b32_e32 v108, v0
	v_cmp_le_i32_e32 vcc, v127, v118
	s_waitcnt vmcnt(7) lgkmcnt(1)
	v_mfma_f32_16x16x32_bf16 v[58:61], v[50:53], v[2:5], 0
	v_add_u32_e32 v150, 2, v127
	v_add_u32_e32 v151, 3, v127
	v_add_u32_e32 v152, 17, v127
	s_waitcnt vmcnt(5)
	v_mfma_f32_16x16x32_bf16 v[50:53], v[50:53], v[10:13], 0
	v_add_u32_e32 v153, 18, v127
	v_add_u32_e32 v154, 19, v127
	v_add_u32_e32 v155, 32, v127
	s_waitcnt lgkmcnt(0)
	v_mfma_f32_16x16x32_bf16 v[78:81], v[54:57], v[6:9], v[58:61]
	v_add_u32_e32 v156, 33, v127
	v_add_u32_e32 v157, 34, v127
	v_add_u32_e32 v158, 35, v127
	s_waitcnt vmcnt(4)
	v_mfma_f32_16x16x32_bf16 v[70:73], v[54:57], v[14:17], v[50:53]
	s_nop 2
	ds_read_b128 v[50:53], v126 offset:2304
	ds_read_b128 v[54:57], v126 offset:2368
	v_add_u32_e32 v159, 48, v127
	v_subrev_u32_e32 v128, 64, v109
	s_waitcnt lgkmcnt(1)
	v_mfma_f32_16x16x32_bf16 v[58:61], v[50:53], v[2:5], 0
	v_cmp_gt_i32_e64 s[62:63], s26, v128
	v_add_u32_e32 v160, 49, v127
	v_add_u32_e32 v161, 50, v127
	v_mfma_f32_16x16x32_bf16 v[50:53], v[50:53], v[10:13], 0
	v_add_u32_e32 v162, 51, v127
	s_add_i32 s9, s9, 1
	s_waitcnt lgkmcnt(0)
	v_mfma_f32_16x16x32_bf16 v[82:85], v[54:57], v[6:9], v[58:61]
	v_mfma_f32_16x16x32_bf16 v[66:69], v[54:57], v[14:17], v[50:53]
	s_nop 2
	ds_read_b128 v[50:53], v126 offset:4608
	ds_read_b128 v[58:61], v126 offset:4672
	s_waitcnt lgkmcnt(1)
	v_mfma_f32_16x16x32_bf16 v[54:57], v[50:53], v[2:5], 0
	v_mfma_f32_16x16x32_bf16 v[50:53], v[50:53], v[10:13], 0
	s_waitcnt lgkmcnt(0)
	v_mfma_f32_16x16x32_bf16 v[54:57], v[58:61], v[6:9], v[54:57]
	v_mfma_f32_16x16x32_bf16 v[62:65], v[58:61], v[14:17], v[50:53]
	ds_read_b128 v[58:61], v126 offset:6912
	ds_read_b128 v[74:77], v126 offset:6976
	v_add_u32_e32 v126, 0x4800, v126
	s_waitcnt lgkmcnt(1)
	v_mfma_f32_16x16x32_bf16 v[50:53], v[58:61], v[2:5], 0
	v_mfma_f32_16x16x32_bf16 v[58:61], v[58:61], v[10:13], 0
	s_waitcnt lgkmcnt(0)
	v_mfma_f32_16x16x32_bf16 v[50:53], v[74:77], v[6:9], v[50:53]
	v_mfma_f32_16x16x32_bf16 v[58:61], v[74:77], v[14:17], v[58:61]
	s_waitcnt vmcnt(3)
	v_mov_b32_e32 v74, v198
	v_mov_b32_e32 v75, v199
	v_mov_b32_e32 v76, v200
	v_mov_b32_e32 v77, v201
	v_sub_u32_e32 v0, v114, v74
	v_med3_i32 v0, v0, 0, v180
	v_lshl_add_u32 v0, v0, 2, s8
	ds_read_b32 v0, v0
	v_sub_u32_e32 v74, v115, v74
	v_med3_i32 v74, v74, 0, v180
	v_lshl_add_u32 v74, v74, 2, s8
	ds_read_b32 v74, v74
	s_waitcnt lgkmcnt(1)
	v_fmac_f32_e32 v0, 0x3e38aa3b, v78
	v_add_u32_e32 v78, -16, v109
	v_cmp_gt_i32_e64 s[0:1], s26, v78
	s_and_b64 vcc, vcc, s[0:1]
	v_cndmask_b32_e32 v104, v181, v0, vcc
	v_sub_u32_e32 v0, v114, v75
	v_med3_i32 v0, v0, 0, v180
	v_lshl_add_u32 v0, v0, 2, s8
	ds_read_b32 v0, v0
	v_subrev_u32_e32 v78, 17, v109
	v_cmp_lt_i32_e64 s[0:1], v127, v118
	v_cmp_gt_i32_e64 s[36:37], s26, v78
	s_and_b64 s[0:1], s[0:1], s[36:37]
	s_waitcnt lgkmcnt(0)
	v_fmac_f32_e32 v0, 0x3e38aa3b, v79
	v_cndmask_b32_e64 v105, v181, v0, s[0:1]
	v_sub_u32_e32 v0, v114, v76
	v_med3_i32 v0, v0, 0, v180
	v_lshl_add_u32 v0, v0, 2, s8
	ds_read_b32 v0, v0
	v_subrev_u32_e32 v78, 18, v109
	v_cmp_le_i32_e64 s[0:1], v150, v118
	v_cmp_gt_i32_e64 s[38:39], s26, v78
	s_and_b64 s[0:1], s[0:1], s[38:39]
	s_waitcnt lgkmcnt(0)
	v_fmac_f32_e32 v0, 0x3e38aa3b, v80
	v_cndmask_b32_e64 v106, v181, v0, s[0:1]
	v_sub_u32_e32 v0, v114, v77
	v_med3_i32 v0, v0, 0, v180
	v_lshl_add_u32 v0, v0, 2, s8
	ds_read_b32 v0, v0
	v_subrev_u32_e32 v78, 19, v109
	v_cmp_gt_i32_e64 s[40:41], s26, v78
	v_cmp_le_i32_e64 s[0:1], v151, v118
	s_and_b64 s[0:1], s[0:1], s[40:41]
	s_waitcnt lgkmcnt(0)
	v_fmac_f32_e32 v0, 0x3e38aa3b, v81
	s_waitcnt vmcnt(2)
	v_mov_b32_e32 v78, v202
	v_mov_b32_e32 v79, v203
	v_mov_b32_e32 v80, v204
	v_mov_b32_e32 v81, v205
	v_cndmask_b32_e64 v107, v181, v0, s[0:1]
	v_add_u32_e32 v0, 16, v127
	v_cmp_le_i32_e64 s[0:1], v0, v118
	v_subrev_u32_e32 v0, 32, v109
	v_cmp_gt_i32_e64 s[42:43], s26, v0
	s_and_b64 s[0:1], s[0:1], s[42:43]
	v_fmac_f32_e32 v74, 0x3e38aa3b, v70
	v_max_f32_e32 v130, v106, v107
	v_sub_u32_e32 v86, v114, v78
	v_med3_i32 v86, v86, 0, v180
	v_lshl_add_u32 v86, v86, 2, s8
	v_sub_u32_e32 v0, v114, v79
	ds_read_b32 v86, v86
	v_med3_i32 v0, v0, 0, v180
	v_lshl_add_u32 v0, v0, 2, s8
	ds_read_b32 v0, v0
	s_waitcnt lgkmcnt(1)
	v_fmac_f32_e32 v86, 0x3e38aa3b, v82
	v_subrev_u32_e32 v82, 33, v109
	v_cndmask_b32_e64 v110, v181, v86, s[0:1]
	v_cmp_le_i32_e64 s[0:1], v152, v118
	v_cmp_gt_i32_e64 s[44:45], s26, v82
	s_waitcnt lgkmcnt(0)
	v_fmac_f32_e32 v0, 0x3e38aa3b, v83
	s_and_b64 s[0:1], s[0:1], s[44:45]
	v_cndmask_b32_e64 v111, v181, v0, s[0:1]
	v_sub_u32_e32 v0, v114, v80
	v_med3_i32 v0, v0, 0, v180
	v_lshl_add_u32 v0, v0, 2, s8
	ds_read_b32 v0, v0
	v_subrev_u32_e32 v82, 34, v109
	v_cmp_le_i32_e64 s[0:1], v153, v118
	v_cmp_gt_i32_e64 s[46:47], s26, v82
	s_and_b64 s[0:1], s[0:1], s[46:47]
	s_waitcnt lgkmcnt(0)
	v_fmac_f32_e32 v0, 0x3e38aa3b, v84
	v_cndmask_b32_e64 v112, v181, v0, s[0:1]
	v_sub_u32_e32 v0, v114, v81
	v_med3_i32 v0, v0, 0, v180
	v_lshl_add_u32 v0, v0, 2, s8
	ds_read_b32 v0, v0
	v_subrev_u32_e32 v82, 35, v109
	v_cmp_gt_i32_e64 s[48:49], s26, v82
	s_waitcnt vmcnt(0)
	v_mov_b32_e32 v86, v210
	v_mov_b32_e32 v87, v211
	v_mov_b32_e32 v88, v212
	v_mov_b32_e32 v89, v213
	v_cmp_le_i32_e64 s[0:1], v154, v118
	s_waitcnt lgkmcnt(0)
; __device__ __forceinline__ void swa_unit(const Ctx& C, const Params& p, int l, int unit) {
;     ...
;                 for (int blk = 0; blk < 4; ++blk) { const int4 t4 = *(const int4*)(p.pos + tok0 + k0 + blk * 16 + fq * 4); const int pkv[4] = {t4.x, t4.y, t4.z, t4.w};
; #pragma unroll
;                     for (int j = 0; j < 4; ++j) { const int key = k0 + blk * 16 + fq * 4 + j; int dd = pq[g] - pkv[j]; dd = dd < 0 ? 0 : (dd > 128 ? 128 : dd);
;                         const float v = s[g][blk][j] * c2 + bth[dd]; const bool ok = (key <= qi) && (qi - key < 128); s[g][blk][j] = ok ? v : -1e30f; } }
;                 float mx = fmaxf(fmaxf(s[g][0][0], s[g][0][1]), fmaxf(s[g][0][2], s[g][0][3]));
; #pragma unroll
;                 for (int blk = 1; blk < 4; ++blk) mx = fmaxf(mx, fmaxf(fmaxf(s[g][blk][0], s[g][blk][1]), fmaxf(s[g][blk][2], s[g][blk][3])));
;                 mx = rowmax4(mx);
;                 const float mn = fmaxf(m[g], mx), alpha = __builtin_amdgcn_exp2f(m[g] - mn); m[g] = mn;
	v_fmac_f32_e32 v0, 0x3e38aa3b, v85
	v_mov_b32_e32 v82, v206
	v_mov_b32_e32 v83, v207
	v_mov_b32_e32 v84, v208
	v_mov_b32_e32 v85, v209
	s_and_b64 s[0:1], s[0:1], s[48:49]
	v_cndmask_b32_e64 v113, v181, v0, s[0:1]
	v_cmp_le_i32_e64 s[0:1], v155, v118
	v_max_f32_e32 v131, v112, v113
	v_max3_f32 v131, v110, v111, v131
	v_sub_u32_e32 v0, v114, v82
	v_med3_i32 v0, v0, 0, v180
	v_lshl_add_u32 v0, v0, 2, s8
	ds_read_b32 v0, v0
	s_waitcnt lgkmcnt(0)
	v_fmac_f32_e32 v0, 0x3e38aa3b, v54
	v_subrev_u32_e32 v54, 48, v109
	v_cmp_gt_i32_e64 s[50:51], s26, v54
	s_and_b64 s[0:1], s[0:1], s[50:51]
	v_cndmask_b32_e64 v54, v181, v0, s[0:1]
	v_sub_u32_e32 v0, v114, v83
	v_med3_i32 v0, v0, 0, v180
	v_lshl_add_u32 v0, v0, 2, s8
	ds_read_b32 v0, v0
	v_cmp_le_i32_e64 s[0:1], v156, v118
	s_waitcnt lgkmcnt(0)
	v_fmac_f32_e32 v0, 0x3e38aa3b, v55
	v_subrev_u32_e32 v55, 49, v109
	v_cmp_gt_i32_e64 s[52:53], s26, v55
	s_and_b64 s[0:1], s[0:1], s[52:53]
	v_cndmask_b32_e64 v55, v181, v0, s[0:1]
	v_sub_u32_e32 v0, v114, v84
	v_med3_i32 v0, v0, 0, v180
	v_lshl_add_u32 v0, v0, 2, s8
	ds_read_b32 v0, v0
	v_cmp_le_i32_e64 s[0:1], v157, v118
	s_waitcnt lgkmcnt(0)
	v_fmac_f32_e32 v0, 0x3e38aa3b, v56
	v_subrev_u32_e32 v56, 50, v109
	v_cmp_gt_i32_e64 s[54:55], s26, v56
	s_and_b64 s[0:1], s[0:1], s[54:55]
	v_cndmask_b32_e64 v56, v181, v0, s[0:1]
	v_sub_u32_e32 v0, v114, v85
	v_med3_i32 v0, v0, 0, v180
	v_lshl_add_u32 v0, v0, 2, s8
	ds_read_b32 v0, v0
	v_cmp_le_i32_e64 s[0:1], v158, v118
	s_waitcnt lgkmcnt(0)
	v_fmac_f32_e32 v0, 0x3e38aa3b, v57
	v_subrev_u32_e32 v57, 51, v109
	v_cmp_gt_i32_e64 s[56:57], s26, v57
	s_and_b64 s[0:1], s[0:1], s[56:57]
	v_cndmask_b32_e64 v57, v181, v0, s[0:1]
	v_sub_u32_e32 v0, v114, v86
	v_med3_i32 v0, v0, 0, v180
	v_lshl_add_u32 v0, v0, 2, s8
	ds_read_b32 v0, v0
	v_cmp_le_i32_e64 s[0:1], v159, v118
	s_and_b64 s[0:1], s[0:1], s[62:63]
	s_waitcnt lgkmcnt(0)
	v_fmac_f32_e32 v0, 0x3e38aa3b, v50
	v_cndmask_b32_e64 v50, v181, v0, s[0:1]
	v_sub_u32_e32 v0, v114, v87
	v_med3_i32 v0, v0, 0, v180
	v_lshl_add_u32 v0, v0, 2, s8
	ds_read_b32 v0, v0
	v_cmp_le_i32_e64 s[0:1], v160, v118
	s_waitcnt lgkmcnt(0)
	v_fmac_f32_e32 v0, 0x3e38aa3b, v51
	v_add_u32_e32 v51, 0xffffffbf, v109
	v_cmp_gt_i32_e64 s[62:63], s26, v51
	s_and_b64 s[0:1], s[0:1], s[62:63]
	v_cndmask_b32_e64 v51, v181, v0, s[0:1]
	v_sub_u32_e32 v0, v114, v88
	v_med3_i32 v0, v0, 0, v180
	v_lshl_add_u32 v0, v0, 2, s8
	ds_read_b32 v0, v0
	v_cmp_le_i32_e64 s[0:1], v161, v118
	s_waitcnt lgkmcnt(0)
	v_fmac_f32_e32 v0, 0x3e38aa3b, v52
	v_add_u32_e32 v52, 0xffffffbe, v109
	v_cmp_gt_i32_e64 s[62:63], s26, v52
	s_and_b64 s[0:1], s[0:1], s[62:63]
	v_cndmask_b32_e64 v52, v181, v0, s[0:1]
	v_sub_u32_e32 v0, v114, v89
	v_med3_i32 v0, v0, 0, v180
	v_lshl_add_u32 v0, v0, 2, s8
	ds_read_b32 v0, v0
	v_cmp_le_i32_e64 s[0:1], v162, v118
	s_waitcnt lgkmcnt(0)
	v_fmac_f32_e32 v0, 0x3e38aa3b, v53
	v_add_u32_e32 v53, 0xffffffbd, v109
	v_cmp_gt_i32_e64 s[62:63], s26, v53
	s_and_b64 s[0:1], s[0:1], s[62:63]
	v_cndmask_b32_e64 v53, v181, v0, s[0:1]
	v_cmp_le_i32_e64 s[0:1], v127, v119
	v_cmp_gt_i32_e64 s[62:63], s26, v109
	s_and_b64 s[0:1], s[0:1], s[62:63]
	v_cndmask_b32_e64 v70, v181, v74, s[0:1]
	v_sub_u32_e32 v74, v115, v75
	v_med3_i32 v74, v74, 0, v180
	v_lshl_add_u32 v74, v74, 2, s8
	ds_read_b32 v74, v74
	v_cmp_lt_i32_e64 s[0:1], v127, v119
	v_max_f32_e32 v0, v104, v105
	v_max3_f32 v0, v0, v130, v131
	v_max_f32_e32 v130, v56, v57
	s_waitcnt lgkmcnt(0)
	v_fmac_f32_e32 v74, 0x3e38aa3b, v71
	v_add_u32_e32 v71, -1, v109
	v_cmp_gt_i32_e64 s[62:63], s26, v71
	s_and_b64 s[0:1], s[0:1], s[62:63]
	v_cndmask_b32_e64 v71, v181, v74, s[0:1]
	v_sub_u32_e32 v74, v115, v76
	v_med3_i32 v74, v74, 0, v180
	v_lshl_add_u32 v74, v74, 2, s8
	ds_read_b32 v74, v74
	v_cmp_le_i32_e64 s[0:1], v150, v119
	v_max_f32_e32 v131, v52, v53
	v_max3_f32 v130, v54, v55, v130
	v_max3_f32 v131, v50, v51, v131
	s_waitcnt lgkmcnt(0)
	v_fmac_f32_e32 v74, 0x3e38aa3b, v72
	v_add_u32_e32 v72, -2, v109
	v_cmp_gt_i32_e64 s[62:63], s26, v72
	s_and_b64 s[0:1], s[0:1], s[62:63]
	v_cndmask_b32_e64 v72, v181, v74, s[0:1]
	v_sub_u32_e32 v74, v115, v77
	v_med3_i32 v74, v74, 0, v180
	v_lshl_add_u32 v74, v74, 2, s8
	ds_read_b32 v74, v74
	v_cmp_le_i32_e64 s[0:1], v151, v119
	v_max3_f32 v0, v0, v130, v131
	v_mov_b32_e32 v130, v0
	s_nop 1
	v_permlane16_swap_b32_e32 v0, v130
	s_waitcnt lgkmcnt(0)
	v_fmac_f32_e32 v74, 0x3e38aa3b, v73
	v_add_u32_e32 v73, -3, v109
	v_cmp_gt_i32_e64 s[62:63], s26, v73
	s_and_b64 s[0:1], s[0:1], s[62:63]
	v_cndmask_b32_e64 v73, v181, v74, s[0:1]
	v_sub_u32_e32 v74, v115, v78
	v_med3_i32 v74, v74, 0, v180
	v_lshl_add_u32 v74, v74, 2, s8
	ds_read_b32 v74, v74
	v_max_f32_e32 v130, v130, v130
	v_max_f32_e32 v0, v0, v0
	v_max_f32_e32 v0, v0, v130
	v_mov_b32_e32 v130, v0
	s_waitcnt lgkmcnt(0)
	v_fmac_f32_e32 v74, 0x3e38aa3b, v66
	v_sub_u32_e32 v66, v115, v79
	v_med3_i32 v66, v66, 0, v180
	v_lshl_add_u32 v66, v66, 2, s8
	ds_read_b32 v66, v66
	v_cndmask_b32_e32 v74, v181, v74, vcc
	v_cmp_le_i32_e32 vcc, v152, v119
	s_and_b64 vcc, vcc, s[36:37]
	v_permlane32_swap_b32_e32 v0, v130
	s_waitcnt lgkmcnt(0)
	v_fmac_f32_e32 v66, 0x3e38aa3b, v67
	v_cndmask_b32_e32 v75, v181, v66, vcc
	v_sub_u32_e32 v66, v115, v80
	v_med3_i32 v66, v66, 0, v180
	v_lshl_add_u32 v66, v66, 2, s8
	ds_read_b32 v66, v66
	v_cmp_le_i32_e32 vcc, v153, v119
	s_and_b64 vcc, vcc, s[38:39]
	v_max_f32_e32 v67, v72, v73
	v_max3_f32 v0, v108, v0, v130
	s_waitcnt lgkmcnt(0)
	v_fmac_f32_e32 v66, 0x3e38aa3b, v68
	v_cndmask_b32_e32 v68, v181, v66, vcc
	v_sub_u32_e32 v66, v115, v81
	v_med3_i32 v66, v66, 0, v180
	v_lshl_add_u32 v66, v66, 2, s8
	ds_read_b32 v66, v66
	v_cmp_le_i32_e32 vcc, v154, v119
	s_and_b64 vcc, vcc, s[40:41]
	v_pk_add_f32 v[104:105], v[104:105], v[0:1] op_sel_hi:[1,0] neg_lo:[0,1] neg_hi:[0,1]
	v_pk_add_f32 v[106:107], v[106:107], v[0:1] op_sel_hi:[1,0] neg_lo:[0,1] neg_hi:[0,1]
	s_waitcnt lgkmcnt(0)
; __device__ __forceinline__ void swa_unit(const Ctx& C, const Params& p, int l, int unit) {
;     ...
;                 for (int blk = 0; blk < 4; ++blk) { const int4 t4 = *(const int4*)(p.pos + tok0 + k0 + blk * 16 + fq * 4); const int pkv[4] = {t4.x, t4.y, t4.z, t4.w};
; #pragma unroll
;                     for (int j = 0; j < 4; ++j) { const int key = k0 + blk * 16 + fq * 4 + j; int dd = pq[g] - pkv[j]; dd = dd < 0 ? 0 : (dd > 128 ? 128 : dd);
;                         const float v = s[g][blk][j] * c2 + bth[dd]; const bool ok = (key <= qi) && (qi - key < 128); s[g][blk][j] = ok ? v : -1e30f; } }
;                 float mx = fmaxf(fmaxf(s[g][0][0], s[g][0][1]), fmaxf(s[g][0][2], s[g][0][3]));
; #pragma unroll
;                 for (int blk = 1; blk < 4; ++blk) mx = fmaxf(mx, fmaxf(fmaxf(s[g][blk][0], s[g][blk][1]), fmaxf(s[g][blk][2], s[g][blk][3])));
;                 mx = rowmax4(mx);
;                 const float mn = fmaxf(m[g], mx), alpha = __builtin_amdgcn_exp2f(m[g] - mn); m[g] = mn;
;                 f32x2 ps2 = (f32x2){0.f, 0.f}; const f32x2 mnv = (f32x2){mn, mn};
; #pragma unroll
;                 for (int blk = 0; blk < 4; ++blk)
; #pragma unroll
;                     for (int jp = 0; jp < 2; ++jp) { f32x2 x = (f32x2){s[g][blk][2 * jp], s[g][blk][2 * jp + 1]}; x = x - mnv;
;                         f32x2 pv; pv.x = __builtin_amdgcn_exp2f(x.x); pv.y = __builtin_amdgcn_exp2f(x.y); ps2 = ps2 + pv; s[g][blk][2 * jp] = pv.x; s[g][blk][2 * jp + 1] = pv.y; }
;                 const float ps = ps2.x + ps2.y;
;                 lsum[g] = lsum[g] * alpha + ps;
	v_fmac_f32_e32 v66, 0x3e38aa3b, v69
	v_cndmask_b32_e32 v69, v181, v66, vcc
	v_sub_u32_e32 v66, v115, v82
	v_med3_i32 v66, v66, 0, v180
	v_lshl_add_u32 v66, v66, 2, s8
	ds_read_b32 v66, v66
	v_cmp_le_i32_e32 vcc, v155, v119
	s_and_b64 vcc, vcc, s[42:43]
	v_max_f32_e32 v76, v68, v69
	v_max3_f32 v76, v74, v75, v76
	s_waitcnt lgkmcnt(0)
	v_fmac_f32_e32 v66, 0x3e38aa3b, v62
	v_cndmask_b32_e32 v62, v181, v66, vcc
	v_sub_u32_e32 v66, v115, v83
	v_med3_i32 v66, v66, 0, v180
	v_lshl_add_u32 v66, v66, 2, s8
	ds_read_b32 v66, v66
	v_cmp_le_i32_e32 vcc, v156, v119
	s_and_b64 vcc, vcc, s[44:45]
	v_exp_f32_e32 v130, v104
	v_exp_f32_e32 v131, v105
	s_waitcnt lgkmcnt(0)
	v_fmac_f32_e32 v66, 0x3e38aa3b, v63
	v_cndmask_b32_e32 v63, v181, v66, vcc
	v_sub_u32_e32 v66, v115, v84
	v_med3_i32 v66, v66, 0, v180
	v_lshl_add_u32 v66, v66, 2, s8
	ds_read_b32 v66, v66
	v_cmp_le_i32_e32 vcc, v157, v119
	s_and_b64 vcc, vcc, s[46:47]
	v_exp_f32_e32 v106, v106
	v_exp_f32_e32 v107, v107
	s_waitcnt lgkmcnt(0)
	v_fmac_f32_e32 v66, 0x3e38aa3b, v64
	v_cndmask_b32_e32 v64, v181, v66, vcc
	v_sub_u32_e32 v66, v115, v85
	v_med3_i32 v66, v66, 0, v180
	v_lshl_add_u32 v66, v66, 2, s8
	ds_read_b32 v66, v66
	v_cmp_le_i32_e32 vcc, v158, v119
	s_and_b64 vcc, vcc, s[48:49]
	v_pk_add_f32 v[110:111], v[110:111], v[0:1] op_sel_hi:[1,0] neg_lo:[0,1] neg_hi:[0,1]
	v_pk_add_f32 v[112:113], v[112:113], v[0:1] op_sel_hi:[1,0] neg_lo:[0,1] neg_hi:[0,1]
	s_waitcnt lgkmcnt(0)
	v_fmac_f32_e32 v66, 0x3e38aa3b, v65
	v_cndmask_b32_e32 v65, v181, v66, vcc
	v_sub_u32_e32 v66, v115, v86
	v_med3_i32 v66, v66, 0, v180
	v_lshl_add_u32 v66, v66, 2, s8
	ds_read_b32 v66, v66
	v_cmp_le_i32_e32 vcc, v159, v119
	s_and_b64 vcc, vcc, s[50:51]
	v_exp_f32_e32 v110, v110
	v_exp_f32_e32 v111, v111
	s_waitcnt lgkmcnt(0)
	v_fmac_f32_e32 v66, 0x3e38aa3b, v58
	v_cndmask_b32_e32 v58, v181, v66, vcc
	v_sub_u32_e32 v66, v115, v87
	v_med3_i32 v66, v66, 0, v180
	v_lshl_add_u32 v66, v66, 2, s8
	ds_read_b32 v66, v66
	v_cmp_le_i32_e32 vcc, v160, v119
	s_and_b64 vcc, vcc, s[52:53]
	v_exp_f32_e32 v112, v112
	v_exp_f32_e32 v113, v113
	s_waitcnt lgkmcnt(0)
	v_fmac_f32_e32 v66, 0x3e38aa3b, v59
	v_cndmask_b32_e32 v59, v181, v66, vcc
	v_sub_u32_e32 v66, v115, v88
	v_med3_i32 v66, v66, 0, v180
	v_lshl_add_u32 v66, v66, 2, s8
	ds_read_b32 v66, v66
	v_cmp_le_i32_e32 vcc, v161, v119
	s_and_b64 vcc, vcc, s[54:55]
	v_pk_add_f32 v[54:55], v[54:55], v[0:1] op_sel_hi:[1,0] neg_lo:[0,1] neg_hi:[0,1]
	v_pk_add_f32 v[104:105], v[130:131], 0 op_sel_hi:[1,0]
	s_waitcnt lgkmcnt(0)
	v_fmac_f32_e32 v66, 0x3e38aa3b, v60
	v_cndmask_b32_e32 v60, v181, v66, vcc
	v_sub_u32_e32 v66, v115, v89
	v_med3_i32 v66, v66, 0, v180
	v_lshl_add_u32 v66, v66, 2, s8
	ds_read_b32 v66, v66
	v_cmp_le_i32_e32 vcc, v162, v119
	s_and_b64 vcc, vcc, s[56:57]
	v_exp_f32_e32 v132, v54
	v_exp_f32_e32 v133, v55
	s_waitcnt lgkmcnt(0)
; #define LAS __attribute__((address_space(3)))
; __device__ __forceinline__ unsigned pkhw(float lo, float hi) { f32x2q v = {lo, hi}; bf16x2q b = __builtin_convertvector(v, bf16x2q); return __builtin_bit_cast(unsigned, b); }
; __device__ __forceinline__ void swa_unit(const Ctx& C, const Params& p, int l, int unit) {
;     ...
;                 float mx = fmaxf(fmaxf(s[g][0][0], s[g][0][1]), fmaxf(s[g][0][2], s[g][0][3]));
; #pragma unroll
;                 for (int blk = 1; blk < 4; ++blk) mx = fmaxf(mx, fmaxf(fmaxf(s[g][blk][0], s[g][blk][1]), fmaxf(s[g][blk][2], s[g][blk][3])));
;                 mx = rowmax4(mx);
;                 const float mn = fmaxf(m[g], mx), alpha = __builtin_amdgcn_exp2f(m[g] - mn); m[g] = mn;
;                 f32x2 ps2 = (f32x2){0.f, 0.f}; const f32x2 mnv = (f32x2){mn, mn};
; #pragma unroll
;                 for (int blk = 0; blk < 4; ++blk)
; #pragma unroll
;                     for (int jp = 0; jp < 2; ++jp) { f32x2 x = (f32x2){s[g][blk][2 * jp], s[g][blk][2 * jp + 1]}; x = x - mnv;
;                         f32x2 pv; pv.x = __builtin_amdgcn_exp2f(x.x); pv.y = __builtin_amdgcn_exp2f(x.y); ps2 = ps2 + pv; s[g][blk][2 * jp] = pv.x; s[g][blk][2 * jp + 1] = pv.y; }
;                 const float ps = ps2.x + ps2.y;
;                 lsum[g] = lsum[g] * alpha + ps;
; #pragma unroll
;                 for (int d = 0; d < 4; ++d) o[g][d] = o[g][d] * alpha;
; #pragma unroll
;                 for (int hf = 0; hf < 2; ++hf) { v4u pw; pw.x = pkhw(s[g][2 * hf][0], s[g][2 * hf][1]); pw.y = pkhw(s[g][2 * hf][2], s[g][2 * hf][3]); pw.z = pkhw(s[g][2 * hf + 1][0], s[g][2 * hf + 1][1]); pw.w = pkhw(s[g][2 * hf + 1][2], s[g][2 * hf + 1][3]);
;                     pf[g][hf] = __builtin_bit_cast(bf16x8, pw); }
;             }
; #pragma unroll
;             for (int hf = 0; hf < 2; ++hf)
; #pragma unroll
;                 for (int d = 0; d < 4; ++d) {
;                     const LAS unsigned char* vp = Vb + (d * 16 + fr) * SROW + (hf * 32 + fq * 4) * 2;
;                     const v2u lo = *(const LAS v2u*)vp, hi = *(const LAS v2u*)(vp + 32);
;                     const v4u vw = (v4u){lo.x, lo.y, hi.x, hi.y}; const bf16x8 vf = __builtin_bit_cast(bf16x8, vw);
; #pragma unroll
;                     for (int g = 0; g < 2; ++g) o[g][d] = __builtin_amdgcn_mfma_f32_16x16x32_bf16(vf, pf[g][hf], o[g][d], 0, 0, 0);
;                 }
	v_fmac_f32_e32 v66, 0x3e38aa3b, v61
	v_cndmask_b32_e32 v61, v181, v66, vcc
	v_max_f32_e32 v66, v70, v71
	v_max3_f32 v66, v66, v67, v76
	v_max_f32_e32 v67, v64, v65
	v_max_f32_e32 v76, v60, v61
	v_max3_f32 v67, v62, v63, v67
	v_max3_f32 v76, v58, v59, v76
	v_max3_f32 v66, v66, v67, v76
	v_mov_b32_e32 v67, v66
	s_nop 1
	v_permlane16_swap_b32_e32 v66, v67
	v_max_f32_e32 v67, v67, v67
	v_max_f32_e32 v66, v66, v66
	v_max_f32_e32 v66, v66, v67
	v_mov_b32_e32 v67, v66
	s_nop 1
	v_permlane32_swap_b32_e32 v66, v67
	v_max3_f32 v66, v129, v66, v67
	v_sub_f32_e32 v67, v129, v66
	v_pk_add_f32 v[70:71], v[70:71], v[66:67] op_sel_hi:[1,0] neg_lo:[0,1] neg_hi:[0,1]
	v_pk_add_f32 v[72:73], v[72:73], v[66:67] op_sel_hi:[1,0] neg_lo:[0,1] neg_hi:[0,1]
	v_exp_f32_e32 v70, v70
	v_exp_f32_e32 v71, v71
	v_exp_f32_e32 v72, v72
	v_exp_f32_e32 v73, v73
	v_pk_add_f32 v[74:75], v[74:75], v[66:67] op_sel_hi:[1,0] neg_lo:[0,1] neg_hi:[0,1]
	v_pk_add_f32 v[68:69], v[68:69], v[66:67] op_sel_hi:[1,0] neg_lo:[0,1] neg_hi:[0,1]
	v_exp_f32_e32 v74, v74
	v_exp_f32_e32 v75, v75
	v_exp_f32_e32 v68, v68
	v_exp_f32_e32 v69, v69
	v_pk_add_f32 v[62:63], v[62:63], v[66:67] op_sel_hi:[1,0] neg_lo:[0,1] neg_hi:[0,1]
	v_pk_add_f32 v[76:77], v[70:71], 0 op_sel_hi:[1,0]
	v_exp_f32_e32 v78, v62
	v_exp_f32_e32 v79, v63
	v_pk_add_f32 v[76:77], v[72:73], v[76:77]
	v_pk_add_f32 v[56:57], v[56:57], v[0:1] op_sel_hi:[1,0] neg_lo:[0,1] neg_hi:[0,1]
	v_pk_add_f32 v[76:77], v[74:75], v[76:77]
	v_pk_add_f32 v[64:65], v[64:65], v[66:67] op_sel_hi:[1,0] neg_lo:[0,1] neg_hi:[0,1]
	v_pk_add_f32 v[76:77], v[68:69], v[76:77]
	v_pk_add_f32 v[104:105], v[106:107], v[104:105]
	v_exp_f32_e32 v164, v56
	v_exp_f32_e32 v165, v57
	v_pk_add_f32 v[50:51], v[50:51], v[0:1] op_sel_hi:[1,0] neg_lo:[0,1] neg_hi:[0,1]
	v_pk_add_f32 v[62:63], v[78:79], v[76:77]
	v_exp_f32_e32 v76, v64
	v_exp_f32_e32 v77, v65
	v_pk_add_f32 v[58:59], v[58:59], v[66:67] op_sel_hi:[1,0] neg_lo:[0,1] neg_hi:[0,1]
	v_pk_add_f32 v[104:105], v[110:111], v[104:105]
	v_exp_f32_e32 v166, v50
	v_exp_f32_e32 v167, v51
	v_pk_add_f32 v[52:53], v[52:53], v[0:1] op_sel_hi:[1,0] neg_lo:[0,1] neg_hi:[0,1]
	v_exp_f32_e32 v80, v58
	v_exp_f32_e32 v81, v59
	v_pk_add_f32 v[60:61], v[60:61], v[66:67] op_sel_hi:[1,0] neg_lo:[0,1] neg_hi:[0,1]
	v_sub_f32_e32 v108, v108, v0
	v_pk_add_f32 v[104:105], v[112:113], v[104:105]
	v_exp_f32_e32 v168, v52
	v_exp_f32_e32 v169, v53
	v_exp_f32_e32 v82, v60
	v_exp_f32_e32 v83, v61
	v_exp_f32_e32 v108, v108
	v_pk_add_f32 v[54:55], v[132:133], v[104:105]
	v_exp_f32_e32 v109, v67
	v_pk_add_f32 v[54:55], v[164:165], v[54:55]
	v_pk_add_f32 v[62:63], v[76:77], v[62:63]
	v_pk_add_f32 v[50:51], v[166:167], v[54:55]
	v_pk_add_f32 v[58:59], v[80:81], v[62:63]
	v_pk_add_f32 v[104:105], v[168:169], v[50:51]
	v_pk_add_f32 v[62:63], v[82:83], v[58:59]
	v_pk_mul_f32 v[58:59], v[46:47], v[108:109] op_sel_hi:[1,0]
	v_mov_b32_e32 v46, v104
	v_mov_b32_e32 v47, v62
	v_mov_b32_e32 v62, v105
	v_pk_add_f32 v[46:47], v[46:47], v[62:63]
	v_mov_b32_e32 v84, v109
	v_pk_mul_f32 v[60:61], v[48:49], v[108:109] op_sel_hi:[1,0]
	v_pk_fma_f32 v[100:101], v[100:101], v[108:109], v[46:47]
	v_pk_mul_f32 v[48:49], v[28:29], v[84:85] op_sel_hi:[1,0]
	v_pk_mul_f32 v[46:47], v[26:27], v[84:85] op_sel_hi:[1,0]
	v_cvt_pk_bf16_f32 v26, v70, v71
	v_cvt_pk_bf16_f32 v29, v68, v69
	ds_read2_b64 v[68:71], v125 offset1:4
	v_cvt_pk_bf16_f32 v54, v130, v131
	v_cvt_pk_bf16_f32 v55, v106, v107
	v_cvt_pk_bf16_f32 v56, v110, v111
	v_cvt_pk_bf16_f32 v57, v112, v113
	v_pk_mul_f32 v[64:65], v[32:33], v[84:85] op_sel_hi:[1,0]
	v_pk_mul_f32 v[62:63], v[30:31], v[84:85] op_sel_hi:[1,0]
	v_cvt_pk_bf16_f32 v27, v72, v73
	v_cvt_pk_bf16_f32 v28, v74, v75
	v_add_u32_e32 v67, 0x800, v125
	s_waitcnt lgkmcnt(0)
	v_mfma_f32_16x16x32_bf16 v[58:61], v[68:71], v[54:57], v[58:61]
	v_mul_f32_e64 v44, v44, v108
	v_mul_f32_e64 v45, v45, v108
	v_pk_mul_f32 v[42:43], v[42:43], v[108:109] op_sel_hi:[1,0]
	v_pk_mul_f32 v[30:31], v[22:23], v[84:85] op_sel_hi:[1,0]
	v_mfma_f32_16x16x32_bf16 v[62:65], v[68:71], v[26:29], v[62:65]
	ds_read2_b64 v[68:71], v67 offset0:32 offset1:36
	v_pk_mul_f32 v[22:23], v[18:19], v[84:85] op_sel_hi:[1,0]
	v_cvt_pk_bf16_f32 v19, v76, v77
	v_add_u32_e32 v76, 0x1000, v125
	s_waitcnt lgkmcnt(0)
	v_mfma_f32_16x16x32_bf16 v[42:45], v[68:71], v[54:57], v[42:45]
	v_mul_f32_e64 v32, v24, v84
	v_mul_f32_e64 v33, v25, v84
	v_add_u32_e32 v77, 0x1800, v125
	v_pk_mul_f32 v[40:41], v[40:41], v[108:109] op_sel_hi:[1,0]
	v_mfma_f32_16x16x32_bf16 v[68:71], v[68:71], v[26:29], v[46:49]
	v_mul_f32_e64 v38, v38, v108
	v_mul_f32_e64 v39, v39, v108
	v_pk_mul_f32 v[36:37], v[36:37], v[108:109] op_sel_hi:[1,0]
	v_pk_mul_f32 v[34:35], v[34:35], v[108:109] op_sel_hi:[1,0]
	ds_read2_b64 v[46:49], v76 offset0:64 offset1:68
	s_waitcnt lgkmcnt(0)
	v_mfma_f32_16x16x32_bf16 v[72:75], v[46:49], v[26:29], v[30:33]
	s_nop 2
	ds_read2_b64 v[30:33], v77 offset0:96 offset1:100
	v_pk_mul_f32 v[24:25], v[20:21], v[84:85] op_sel_hi:[1,0]
	v_cvt_pk_bf16_f32 v50, v132, v133
	v_mfma_f32_16x16x32_bf16 v[38:41], v[46:49], v[54:57], v[38:41]
	v_cvt_pk_bf16_f32 v51, v164, v165
	v_cvt_pk_bf16_f32 v52, v166, v167
	v_cvt_pk_bf16_f32 v53, v168, v169
	s_waitcnt lgkmcnt(0)
	v_mfma_f32_16x16x32_bf16 v[34:37], v[30:33], v[54:57], v[34:37]
	v_cvt_pk_bf16_f32 v18, v78, v79
	v_cvt_pk_bf16_f32 v20, v80, v81
	v_cvt_pk_bf16_f32 v21, v82, v83
	v_mfma_f32_16x16x32_bf16 v[54:57], v[30:33], v[26:29], v[22:25]
	s_mov_b64 s[0:1], 0x100
	v_add_u32_e32 v127, 64, v127
	v_lshl_add_u64 v[102:103], v[102:103], 0, s[0:1]
	ds_read2_b64 v[22:25], v125 offset0:8 offset1:12
	s_waitcnt lgkmcnt(0)
	v_mfma_f32_16x16x32_bf16 v[46:49], v[22:25], v[50:53], v[58:61]
	s_nop 2
	ds_read2_b64 v[58:61], v77 offset0:104 offset1:108
	v_add_u32_e32 v125, 0x4800, v125
	s_cmp_ge_i32 s9, s94
	v_mfma_f32_16x16x32_bf16 v[30:33], v[22:25], v[18:21], v[62:65]
	ds_read2_b64 v[22:25], v67 offset0:40 offset1:44
	v_mov_b32_e32 v109, v128
	s_waitcnt lgkmcnt(0)
	v_mfma_f32_16x16x32_bf16 v[42:45], v[22:25], v[50:53], v[42:45]
	v_mfma_f32_16x16x32_bf16 v[26:29], v[22:25], v[18:21], v[68:71]
	ds_read2_b64 v[22:25], v76 offset0:72 offset1:76
	s_waitcnt lgkmcnt(0)
	v_mfma_f32_16x16x32_bf16 v[38:41], v[22:25], v[50:53], v[38:41]
	v_mfma_f32_16x16x32_bf16 v[22:25], v[22:25], v[18:21], v[72:75]
	v_mfma_f32_16x16x32_bf16 v[34:37], v[58:61], v[50:53], v[34:37]
	v_mfma_f32_16x16x32_bf16 v[18:21], v[58:61], v[18:21], v[54:57]
	s_cbranch_scc0 .LBB0_276
	s_mov_b64 s[62:63], s[14:15]
	s_branch .LBB0_273

; __device__ __forceinline__ void mla_unit(const Ctx& C, const Params& p, int unit) {
;     ...
;     for (int kp = 0; kp < nt / 2; ++kp) {
;         const bool more = 2 * kp + 2 < nt;
;         if (more) {
; #pragma unroll
;             for (int sb = 0; sb < 2; ++sb) { const int tn = 2 * kp + 2 + sb; r0[sb] = *(const v4u*)(ksrc0 + (size_t)tn * kstep0); if (has1) r1[sb] = *(const v4u*)(ksrc1 + (size_t)tn * kstep1); r2[sb] = *(const v4u*)(vsrc + (size_t)tn * 64); } }
.LBB0_505:
	s_lshl_b32 s91, s90, 1
	s_add_i32 s88, s91, 2
	s_cmp_lt_i32 s88, s31
	s_cselect_b64 s[20:21], -1, 0
	s_cmp_ge_i32 s88, s31
	s_cbranch_scc1 .LBB0_511
	v_mad_u64_u32 v[20:21], s[0:1], v127, s88, 0
	v_lshl_add_u64 v[20:21], v[20:21], 1, v[122:123]
	global_load_dwordx4 v[20:23], v[20:21], off
	s_and_saveexec_b64 s[0:1], s[36:37]
	s_cbranch_execz .LBB0_508
	v_mad_u64_u32 v[24:25], s[10:11], v126, s88, 0
	v_lshl_add_u64 v[24:25], v[24:25], 1, v[124:125]
	global_load_dwordx4 v[24:27], v[24:25], off
.LBB0_508:
	s_or_b64 exec, exec, s[0:1]
	s_lshl_b64 s[0:1], s[88:89], 7
	s_or_b32 s88, s88, 1
	v_lshl_add_u64 v[32:33], v[128:129], 0, s[0:1]
	v_mad_u64_u32 v[36:37], s[0:1], v127, s88, 0
	v_lshl_add_u64 v[36:37], v[36:37], 1, v[122:123]
	global_load_dwordx4 v[32:35], v[32:33], off
	s_nop 0
	global_load_dwordx4 v[36:39], v[36:37], off
	s_and_saveexec_b64 s[0:1], s[36:37]
	s_cbranch_execz .LBB0_510
	v_mad_u64_u32 v[28:29], s[10:11], v126, s88, 0
	v_lshl_add_u64 v[28:29], v[28:29], 1, v[124:125]
	global_load_dwordx4 v[28:31], v[28:29], off
.LBB0_510:
	s_or_b64 exec, exec, s[0:1]
	s_lshl_b64 s[0:1], s[88:89], 7
	v_lshl_add_u64 v[40:41], v[128:129], 0, s[0:1]
	global_load_dwordx4 v[40:43], v[40:41], off
